# EpiRes epilogue (Wo/Down GEMM): 16 residual loads hoisted with counted vmcnt waits instead of 16 serialized load->vmcnt(0) steps; split-K partial path stores acc directly
# speedup vs baseline: 1.0482x; 1.0085x over previous
; __device__ __forceinline__ unsigned cvtpk(float lo, float hi) { f32x2_t v = {lo, hi}; bf16x2_t b = __builtin_convertvector(v, bf16x2_t); return __builtin_bit_cast(unsigned, b); }
; __device__ __forceinline__ void prologue(LAS unsigned char* lds, int gw, int ngw, int lane, int wave) {
;     ...
;     bf16_t* XB = (bf16_t*)(P->ws + WS_XB);
;     for (int m = gw; m < MT; m += ngw) {
;         const float* xr = m < MP ? P->in[0] + (size_t)m * DM : P->in[1] + (size_t)(m - MP) * DM;
; #pragma unroll
;         for (int q = 0; q < 4; ++q) { const f32x4 v = ((const f32x4*)xr)[lane + 64 * q]; u32x2 w; w.x = cvtpk(v[0], v[1]); w.y = cvtpk(v[2], v[3]); ((u32x2*)(XB + (size_t)m * DM))[lane + 64 * q] = w; }
;     }
.LBB0_26:
	s_load_dwordx2 s[6:7], s[4:5], 0xb0
	s_cmp_gt_i32 s0, 0x80ff
	s_cbranch_scc1 .LBB0_33
	s_load_dwordx2 s[8:9], s[4:5], 0x0
	s_load_dwordx2 s[10:11], s[4:5], 0x8
	v_mov_b32_e32 v5, 0
	v_lshlrev_b32_e32 v1, 4, v2
	s_mov_b32 s19, 0
	s_mov_b32 s14, s0
	s_mov_b64 s[12:13], 0x6400000
	s_waitcnt lgkmcnt(0)
	v_lshl_add_u64 v[4:5], s[6:7], 0, v[4:5]
	v_lshl_add_u64 v[4:5], v[4:5], 0, s[12:13]
	s_cmpk_gt_i32 s14, 0x7fff
	s_cselect_b32 s20, s10, s8
	s_cselect_b32 s21, s11, s9
	s_and_b32 s22, s14, 0x7fff
	s_lshl_b32 s22, s22, 12
	s_add_u32 s16, s20, s22
	s_addc_u32 s17, s21, 0
	s_lshl_b32 s18, s14, 11
	global_load_dwordx4 v[72:75], v1, s[16:17]
	global_load_dwordx4 v[76:79], v1, s[16:17] offset:1024
	global_load_dwordx4 v[80:83], v1, s[16:17] offset:2048
	global_load_dwordx4 v[84:87], v1, s[16:17] offset:3072
	v_lshl_add_u64 v[64:65], v[4:5], 0, s[18:19]
	s_add_i32 s14, s14, s66
	s_cmp_gt_i32 s14, 0x80ff
	s_cbranch_scc1 .Lxb_tailA
	s_cmpk_gt_i32 s14, 0x7fff
	s_cselect_b32 s20, s10, s8
	s_cselect_b32 s21, s11, s9
	s_and_b32 s22, s14, 0x7fff
	s_lshl_b32 s22, s22, 12
	s_add_u32 s16, s20, s22
	s_addc_u32 s17, s21, 0
	s_lshl_b32 s18, s14, 11
	global_load_dwordx4 v[88:91], v1, s[16:17]
	global_load_dwordx4 v[92:95], v1, s[16:17] offset:1024
	global_load_dwordx4 v[96:99], v1, s[16:17] offset:2048
	global_load_dwordx4 v[100:103], v1, s[16:17] offset:3072
	v_lshl_add_u64 v[66:67], v[4:5], 0, s[18:19]
	s_waitcnt vmcnt(4)
	v_cvt_pk_bf16_f32 v72, v72, v73
	v_cvt_pk_bf16_f32 v73, v74, v75
	v_cvt_pk_bf16_f32 v76, v76, v77
	v_cvt_pk_bf16_f32 v77, v78, v79
	v_cvt_pk_bf16_f32 v80, v80, v81
	v_cvt_pk_bf16_f32 v81, v82, v83
	v_cvt_pk_bf16_f32 v84, v84, v85
	v_cvt_pk_bf16_f32 v85, v86, v87
	global_store_dwordx2 v[64:65], v[72:73], off
	global_store_dwordx2 v[64:65], v[76:77], off offset:512
	global_store_dwordx2 v[64:65], v[80:81], off offset:1024
	global_store_dwordx2 v[64:65], v[84:85], off offset:1536
.Lxb_loop:
	s_add_i32 s14, s14, s66
	s_cmp_gt_i32 s14, 0x80ff
	s_cbranch_scc1 .Lxb_tailB
	s_cmpk_gt_i32 s14, 0x7fff
	s_cselect_b32 s20, s10, s8
	s_cselect_b32 s21, s11, s9
	s_and_b32 s22, s14, 0x7fff
	s_lshl_b32 s22, s22, 12
	s_add_u32 s16, s20, s22
	s_addc_u32 s17, s21, 0
	s_lshl_b32 s18, s14, 11
	global_load_dwordx4 v[72:75], v1, s[16:17]
	global_load_dwordx4 v[76:79], v1, s[16:17] offset:1024
	global_load_dwordx4 v[80:83], v1, s[16:17] offset:2048
	global_load_dwordx4 v[84:87], v1, s[16:17] offset:3072
	v_lshl_add_u64 v[64:65], v[4:5], 0, s[18:19]
	s_waitcnt vmcnt(8)
	v_cvt_pk_bf16_f32 v88, v88, v89
	v_cvt_pk_bf16_f32 v89, v90, v91
	v_cvt_pk_bf16_f32 v92, v92, v93
	v_cvt_pk_bf16_f32 v93, v94, v95
	v_cvt_pk_bf16_f32 v96, v96, v97
	v_cvt_pk_bf16_f32 v97, v98, v99
	v_cvt_pk_bf16_f32 v100, v100, v101
	v_cvt_pk_bf16_f32 v101, v102, v103
	global_store_dwordx2 v[66:67], v[88:89], off
	global_store_dwordx2 v[66:67], v[92:93], off offset:512
	global_store_dwordx2 v[66:67], v[96:97], off offset:1024
	global_store_dwordx2 v[66:67], v[100:101], off offset:1536
	s_add_i32 s14, s14, s66
	s_cmp_gt_i32 s14, 0x80ff
	s_cbranch_scc1 .Lxb_tailA
	s_cmpk_gt_i32 s14, 0x7fff
	s_cselect_b32 s20, s10, s8
	s_cselect_b32 s21, s11, s9
	s_and_b32 s22, s14, 0x7fff
	s_lshl_b32 s22, s22, 12
	s_add_u32 s16, s20, s22
	s_addc_u32 s17, s21, 0
	s_lshl_b32 s18, s14, 11
	global_load_dwordx4 v[88:91], v1, s[16:17]
	global_load_dwordx4 v[92:95], v1, s[16:17] offset:1024
	global_load_dwordx4 v[96:99], v1, s[16:17] offset:2048
	global_load_dwordx4 v[100:103], v1, s[16:17] offset:3072
	v_lshl_add_u64 v[66:67], v[4:5], 0, s[18:19]
	s_waitcnt vmcnt(8)
	v_cvt_pk_bf16_f32 v72, v72, v73
	v_cvt_pk_bf16_f32 v73, v74, v75
	v_cvt_pk_bf16_f32 v76, v76, v77
	v_cvt_pk_bf16_f32 v77, v78, v79
	v_cvt_pk_bf16_f32 v80, v80, v81
	v_cvt_pk_bf16_f32 v81, v82, v83
	v_cvt_pk_bf16_f32 v84, v84, v85
	v_cvt_pk_bf16_f32 v85, v86, v87
	global_store_dwordx2 v[64:65], v[72:73], off
	global_store_dwordx2 v[64:65], v[76:77], off offset:512
	global_store_dwordx2 v[64:65], v[80:81], off offset:1024
	global_store_dwordx2 v[64:65], v[84:85], off offset:1536
	s_branch .Lxb_loop
.Lxb_tailA:
	s_waitcnt vmcnt(0)
	v_cvt_pk_bf16_f32 v72, v72, v73
	v_cvt_pk_bf16_f32 v73, v74, v75
	v_cvt_pk_bf16_f32 v76, v76, v77
	v_cvt_pk_bf16_f32 v77, v78, v79
	v_cvt_pk_bf16_f32 v80, v80, v81
	v_cvt_pk_bf16_f32 v81, v82, v83
	v_cvt_pk_bf16_f32 v84, v84, v85
	v_cvt_pk_bf16_f32 v85, v86, v87
	global_store_dwordx2 v[64:65], v[72:73], off
	global_store_dwordx2 v[64:65], v[76:77], off offset:512
	global_store_dwordx2 v[64:65], v[80:81], off offset:1024
	global_store_dwordx2 v[64:65], v[84:85], off offset:1536
	s_branch .LBB0_33
.Lxb_tailB:
	s_waitcnt vmcnt(0)
	v_cvt_pk_bf16_f32 v88, v88, v89
	v_cvt_pk_bf16_f32 v89, v90, v91
	v_cvt_pk_bf16_f32 v92, v92, v93
	v_cvt_pk_bf16_f32 v93, v94, v95
	v_cvt_pk_bf16_f32 v96, v96, v97
	v_cvt_pk_bf16_f32 v97, v98, v99
	v_cvt_pk_bf16_f32 v100, v100, v101
	v_cvt_pk_bf16_f32 v101, v102, v103
	global_store_dwordx2 v[66:67], v[88:89], off
	global_store_dwordx2 v[66:67], v[92:93], off offset:512
	global_store_dwordx2 v[66:67], v[96:97], off offset:1024
	global_store_dwordx2 v[66:67], v[100:101], off offset:1536

; __device__ __forceinline__ unsigned cvtpk(float lo, float hi) { f32x2_t v = {lo, hi}; bf16x2_t b = __builtin_convertvector(v, bf16x2_t); return __builtin_bit_cast(unsigned, b); }
;     __device__ __forceinline__ void operator()(const f32x4 (&acc)[2][2][4][2], const pg8::Unit& u, int wr, int wc, int fr, int fq) const {
;         const bool part = u.part >= 0;
;         float* dbase = part ? (float*)(ws + WS_PART) + (size_t)u.part * MS * 1024 : (float*)(ws + WS_XF + (size_t)u.pm * 256 * 2048);
;         const unsigned char* sbase = part ? ws + WS_ZERO : ws + WS_XB + (size_t)u.pm * 256 * 2048;
;         const unsigned sstr = part ? 0u : 2048u;
;         const unsigned cb = (unsigned)(u.pn * 256 + wc * 32 + 8 * fq);
; #pragma unroll
;         for (int ai = 0; ai < 2; ++ai)
; #pragma unroll
;             for (int m = 0; m < 4; ++m) {
;                 const unsigned rl = (unsigned)(ai * 128 + wr * 64 + m * 16 + fr);
; #pragma unroll
;                 for (int bj = 0; bj < 2; ++bj) {
;                     const unsigned so = rl * sstr + (cb + (unsigned)(bj * 128)) * 2u, dofs = rl * 4096u + (cb + (unsigned)(bj * 128)) * 4u;
;                     const u32x4 xb = *(const u32x4*)(sbase + so);
;                     f32x4 x0, x1;
;                     x0[0] = __uint_as_float(xb.x << 16); x0[1] = __uint_as_float(xb.x & 0xffff0000u); x0[2] = __uint_as_float(xb.y << 16); x0[3] = __uint_as_float(xb.y & 0xffff0000u);
;                     x1[0] = __uint_as_float(xb.z << 16); x1[1] = __uint_as_float(xb.z & 0xffff0000u); x1[2] = __uint_as_float(xb.w << 16); x1[3] = __uint_as_float(xb.w & 0xffff0000u);
;                     const f32x4 y0 = x0 * DN_ALPHA + acc[ai][bj][m][0], y1 = x1 * DN_ALPHA + acc[ai][bj][m][1];
;                     if (part) { *(f32x4*)((char*)dbase + dofs) = y0; *(f32x4*)((char*)dbase + dofs + 16) = y1; }
;                     else { u32x4 w; w.x = cvtpk(y0[0], y0[1]); w.y = cvtpk(y0[2], y0[3]); w.z = cvtpk(y1[0], y1[1]); w.w = cvtpk(y1[2], y1[3]); *(u32x4*)((char*)dbase + (dofs >> 1)) = w; }
;                     asm volatile("" ::: "memory");
;                 }
.LBB0_388:
	s_add_u32 s9, s49, s28
	s_addc_u32 s21, s50, s29
	v_lshl_or_b32 v165, s20, 8, v160
	s_and_b64 s[6:7], s[6:7], exec
	v_mul_lo_u32 v164, s15, v138
	v_lshlrev_b32_e32 v162, 1, v165
	s_cselect_b32 s25, s52, s21
	s_cselect_b32 s24, s51, s9
	v_add_u32_e32 v163, v164, v162
	s_and_b64 vcc, exec, s[26:27]
	s_cbranch_vccz .Lerwo_part
	v_lshrrev_b32_e32 v176, 1, v140
	v_add_u32_e32 v176, v176, v162
	global_load_dwordx4 v[198:201], v163, s[24:25]
	global_load_dwordx4 v[202:205], v163, s[24:25] offset:256
	s_add_u32 s28, s24, 0x8000
	s_addc_u32 s29, s25, 0
	global_load_dwordx4 v[206:209], v163, s[28:29]
	global_load_dwordx4 v[210:213], v163, s[28:29] offset:256
	s_add_u32 s28, s24, 0x10000
	s_addc_u32 s29, s25, 0
	global_load_dwordx4 v[214:217], v163, s[28:29]
	global_load_dwordx4 v[218:221], v163, s[28:29] offset:256
	s_add_u32 s28, s24, 0x18000
	s_addc_u32 s29, s25, 0
	global_load_dwordx4 v[222:225], v163, s[28:29]
	global_load_dwordx4 v[226:229], v163, s[28:29] offset:256
	s_add_u32 s28, s24, 0x40000
	s_addc_u32 s29, s25, 0
	global_load_dwordx4 v[230:233], v163, s[28:29]
	global_load_dwordx4 v[234:237], v163, s[28:29] offset:256
	s_add_u32 s28, s24, 0x48000
	s_addc_u32 s29, s25, 0
	global_load_dwordx4 v[238:241], v163, s[28:29]
	global_load_dwordx4 v[242:245], v163, s[28:29] offset:256
	s_add_u32 s28, s24, 0x50000
	s_addc_u32 s29, s25, 0
	global_load_dwordx4 v[246:249], v163, s[28:29]
	global_load_dwordx4 v[164:167], v163, s[28:29] offset:256
	s_add_u32 s28, s24, 0x58000
	s_addc_u32 s29, s25, 0
	global_load_dwordx4 v[168:171], v163, s[28:29]
	global_load_dwordx4 v[172:175], v163, s[28:29] offset:256
	s_waitcnt vmcnt(15)
	v_lshlrev_b32_e32 v177, 16, v198
	v_lshlrev_b32_e32 v180, 16, v199
	v_lshlrev_b32_e32 v181, 16, v200
	v_lshlrev_b32_e32 v250, 16, v201
	v_and_b32_e32 v198, 0xffff0000, v198
	v_and_b32_e32 v199, 0xffff0000, v199
	v_and_b32_e32 v200, 0xffff0000, v200
	v_and_b32_e32 v201, 0xffff0000, v201
	v_fmac_f32_e32 v124, s92, v177
	v_fmac_f32_e32 v125, s92, v198
	v_fmac_f32_e32 v126, s92, v180
	v_fmac_f32_e32 v127, s92, v199
	v_fmac_f32_e32 v120, s92, v181
	v_fmac_f32_e32 v121, s92, v200
	v_fmac_f32_e32 v122, s92, v250
	v_fmac_f32_e32 v123, s92, v201
	v_cvt_pk_bf16_f32 v198, v124, v125
	v_cvt_pk_bf16_f32 v199, v126, v127
	v_cvt_pk_bf16_f32 v200, v120, v121
	v_cvt_pk_bf16_f32 v201, v122, v123
	global_store_dwordx4 v176, v[198:201], s[22:23]
	s_waitcnt vmcnt(15)
	v_lshlrev_b32_e32 v177, 16, v202
	v_lshlrev_b32_e32 v180, 16, v203
	v_lshlrev_b32_e32 v181, 16, v204
	v_lshlrev_b32_e32 v250, 16, v205
	v_and_b32_e32 v202, 0xffff0000, v202
	v_and_b32_e32 v203, 0xffff0000, v203
	v_and_b32_e32 v204, 0xffff0000, v204
	v_and_b32_e32 v205, 0xffff0000, v205
	v_fmac_f32_e32 v116, s92, v177
	v_fmac_f32_e32 v117, s92, v202
	v_fmac_f32_e32 v118, s92, v180
	v_fmac_f32_e32 v119, s92, v203
	v_fmac_f32_e32 v112, s92, v181
	v_fmac_f32_e32 v113, s92, v204
	v_fmac_f32_e32 v114, s92, v250
	v_fmac_f32_e32 v115, s92, v205
	v_cvt_pk_bf16_f32 v202, v116, v117
	v_cvt_pk_bf16_f32 v203, v118, v119
	v_cvt_pk_bf16_f32 v204, v112, v113
	v_cvt_pk_bf16_f32 v205, v114, v115
	global_store_dwordx4 v176, v[202:205], s[22:23] offset:256
	s_add_u32 s30, s22, 0x8000
	s_addc_u32 s31, s23, 0
	s_waitcnt vmcnt(15)
	v_lshlrev_b32_e32 v177, 16, v206
	v_lshlrev_b32_e32 v180, 16, v207
	v_lshlrev_b32_e32 v181, 16, v208
	v_lshlrev_b32_e32 v250, 16, v209
	v_and_b32_e32 v206, 0xffff0000, v206
	v_and_b32_e32 v207, 0xffff0000, v207
	v_and_b32_e32 v208, 0xffff0000, v208
	v_and_b32_e32 v209, 0xffff0000, v209
	v_fmac_f32_e32 v108, s92, v177
	v_fmac_f32_e32 v109, s92, v206
	v_fmac_f32_e32 v110, s92, v180
	v_fmac_f32_e32 v111, s92, v207
	v_fmac_f32_e32 v104, s92, v181
	v_fmac_f32_e32 v105, s92, v208
	v_fmac_f32_e32 v106, s92, v250
	v_fmac_f32_e32 v107, s92, v209
	v_cvt_pk_bf16_f32 v206, v108, v109
	v_cvt_pk_bf16_f32 v207, v110, v111
	v_cvt_pk_bf16_f32 v208, v104, v105
	v_cvt_pk_bf16_f32 v209, v106, v107
	global_store_dwordx4 v176, v[206:209], s[30:31]
	s_waitcnt vmcnt(15)
	v_lshlrev_b32_e32 v177, 16, v210
	v_lshlrev_b32_e32 v180, 16, v211
	v_lshlrev_b32_e32 v181, 16, v212
	v_lshlrev_b32_e32 v250, 16, v213
	v_and_b32_e32 v210, 0xffff0000, v210
	v_and_b32_e32 v211, 0xffff0000, v211
	v_and_b32_e32 v212, 0xffff0000, v212
	v_and_b32_e32 v213, 0xffff0000, v213
	v_fmac_f32_e32 v100, s92, v177
	v_fmac_f32_e32 v101, s92, v210
	v_fmac_f32_e32 v102, s92, v180
	v_fmac_f32_e32 v103, s92, v211
	v_fmac_f32_e32 v96, s92, v181
	v_fmac_f32_e32 v97, s92, v212
	v_fmac_f32_e32 v98, s92, v250
	v_fmac_f32_e32 v99, s92, v213
	v_cvt_pk_bf16_f32 v210, v100, v101
	v_cvt_pk_bf16_f32 v211, v102, v103
	v_cvt_pk_bf16_f32 v212, v96, v97
	v_cvt_pk_bf16_f32 v213, v98, v99
	global_store_dwordx4 v176, v[210:213], s[30:31] offset:256
	s_add_u32 s30, s22, 0x10000
	s_addc_u32 s31, s23, 0
	s_waitcnt vmcnt(15)
	v_lshlrev_b32_e32 v177, 16, v214
	v_lshlrev_b32_e32 v180, 16, v215
	v_lshlrev_b32_e32 v181, 16, v216
	v_lshlrev_b32_e32 v250, 16, v217
	v_and_b32_e32 v214, 0xffff0000, v214
	v_and_b32_e32 v215, 0xffff0000, v215
	v_and_b32_e32 v216, 0xffff0000, v216
	v_and_b32_e32 v217, 0xffff0000, v217
	v_fmac_f32_e32 v92, s92, v177
	v_fmac_f32_e32 v93, s92, v214
	v_fmac_f32_e32 v94, s92, v180
	v_fmac_f32_e32 v95, s92, v215
	v_fmac_f32_e32 v88, s92, v181
	v_fmac_f32_e32 v89, s92, v216
	v_fmac_f32_e32 v90, s92, v250
	v_fmac_f32_e32 v91, s92, v217
	v_cvt_pk_bf16_f32 v214, v92, v93
	v_cvt_pk_bf16_f32 v215, v94, v95
	v_cvt_pk_bf16_f32 v216, v88, v89
	v_cvt_pk_bf16_f32 v217, v90, v91
	global_store_dwordx4 v176, v[214:217], s[30:31]
	s_waitcnt vmcnt(15)
; __device__ __forceinline__ unsigned cvtpk(float lo, float hi) { f32x2_t v = {lo, hi}; bf16x2_t b = __builtin_convertvector(v, bf16x2_t); return __builtin_bit_cast(unsigned, b); }
;     __device__ __forceinline__ void operator()(const f32x4 (&acc)[2][2][4][2], const pg8::Unit& u, int wr, int wc, int fr, int fq) const {
;     ...
;                     const unsigned so = rl * sstr + (cb + (unsigned)(bj * 128)) * 2u, dofs = rl * 4096u + (cb + (unsigned)(bj * 128)) * 4u;
;                     const u32x4 xb = *(const u32x4*)(sbase + so);
;                     f32x4 x0, x1;
;                     x0[0] = __uint_as_float(xb.x << 16); x0[1] = __uint_as_float(xb.x & 0xffff0000u); x0[2] = __uint_as_float(xb.y << 16); x0[3] = __uint_as_float(xb.y & 0xffff0000u);
;                     x1[0] = __uint_as_float(xb.z << 16); x1[1] = __uint_as_float(xb.z & 0xffff0000u); x1[2] = __uint_as_float(xb.w << 16); x1[3] = __uint_as_float(xb.w & 0xffff0000u);
;                     const f32x4 y0 = x0 * DN_ALPHA + acc[ai][bj][m][0], y1 = x1 * DN_ALPHA + acc[ai][bj][m][1];
;                     if (part) { *(f32x4*)((char*)dbase + dofs) = y0; *(f32x4*)((char*)dbase + dofs + 16) = y1; }
;                     else { u32x4 w; w.x = cvtpk(y0[0], y0[1]); w.y = cvtpk(y0[2], y0[3]); w.z = cvtpk(y1[0], y1[1]); w.w = cvtpk(y1[2], y1[3]); *(u32x4*)((char*)dbase + (dofs >> 1)) = w; }
	v_lshlrev_b32_e32 v177, 16, v218
	v_lshlrev_b32_e32 v180, 16, v219
	v_lshlrev_b32_e32 v181, 16, v220
	v_lshlrev_b32_e32 v250, 16, v221
	v_and_b32_e32 v218, 0xffff0000, v218
	v_and_b32_e32 v219, 0xffff0000, v219
	v_and_b32_e32 v220, 0xffff0000, v220
	v_and_b32_e32 v221, 0xffff0000, v221
	v_fmac_f32_e32 v84, s92, v177
	v_fmac_f32_e32 v85, s92, v218
	v_fmac_f32_e32 v86, s92, v180
	v_fmac_f32_e32 v87, s92, v219
	v_fmac_f32_e32 v80, s92, v181
	v_fmac_f32_e32 v81, s92, v220
	v_fmac_f32_e32 v82, s92, v250
	v_fmac_f32_e32 v83, s92, v221
	v_cvt_pk_bf16_f32 v218, v84, v85
	v_cvt_pk_bf16_f32 v219, v86, v87
	v_cvt_pk_bf16_f32 v220, v80, v81
	v_cvt_pk_bf16_f32 v221, v82, v83
	global_store_dwordx4 v176, v[218:221], s[30:31] offset:256
	s_add_u32 s30, s22, 0x18000
	s_addc_u32 s31, s23, 0
	s_waitcnt vmcnt(15)
	v_lshlrev_b32_e32 v177, 16, v222
	v_lshlrev_b32_e32 v180, 16, v223
	v_lshlrev_b32_e32 v181, 16, v224
	v_lshlrev_b32_e32 v250, 16, v225
	v_and_b32_e32 v222, 0xffff0000, v222
	v_and_b32_e32 v223, 0xffff0000, v223
	v_and_b32_e32 v224, 0xffff0000, v224
	v_and_b32_e32 v225, 0xffff0000, v225
	v_fmac_f32_e32 v76, s92, v177
	v_fmac_f32_e32 v77, s92, v222
	v_fmac_f32_e32 v78, s92, v180
	v_fmac_f32_e32 v79, s92, v223
	v_fmac_f32_e32 v72, s92, v181
	v_fmac_f32_e32 v73, s92, v224
	v_fmac_f32_e32 v74, s92, v250
	v_fmac_f32_e32 v75, s92, v225
	v_cvt_pk_bf16_f32 v222, v76, v77
	v_cvt_pk_bf16_f32 v223, v78, v79
	v_cvt_pk_bf16_f32 v224, v72, v73
	v_cvt_pk_bf16_f32 v225, v74, v75
	global_store_dwordx4 v176, v[222:225], s[30:31]
	s_waitcnt vmcnt(15)
	v_lshlrev_b32_e32 v177, 16, v226
	v_lshlrev_b32_e32 v180, 16, v227
	v_lshlrev_b32_e32 v181, 16, v228
	v_lshlrev_b32_e32 v250, 16, v229
	v_and_b32_e32 v226, 0xffff0000, v226
	v_and_b32_e32 v227, 0xffff0000, v227
	v_and_b32_e32 v228, 0xffff0000, v228
	v_and_b32_e32 v229, 0xffff0000, v229
	v_fmac_f32_e32 v68, s92, v177
	v_fmac_f32_e32 v69, s92, v226
	v_fmac_f32_e32 v70, s92, v180
	v_fmac_f32_e32 v71, s92, v227
	v_fmac_f32_e32 v64, s92, v181
	v_fmac_f32_e32 v65, s92, v228
	v_fmac_f32_e32 v66, s92, v250
	v_fmac_f32_e32 v67, s92, v229
	v_cvt_pk_bf16_f32 v226, v68, v69
	v_cvt_pk_bf16_f32 v227, v70, v71
	v_cvt_pk_bf16_f32 v228, v64, v65
	v_cvt_pk_bf16_f32 v229, v66, v67
	global_store_dwordx4 v176, v[226:229], s[30:31] offset:256
	s_add_u32 s30, s22, 0x40000
	s_addc_u32 s31, s23, 0
	s_waitcnt vmcnt(15)
	v_lshlrev_b32_e32 v177, 16, v230
	v_lshlrev_b32_e32 v180, 16, v231
	v_lshlrev_b32_e32 v181, 16, v232
	v_lshlrev_b32_e32 v250, 16, v233
	v_and_b32_e32 v230, 0xffff0000, v230
	v_and_b32_e32 v231, 0xffff0000, v231
	v_and_b32_e32 v232, 0xffff0000, v232
	v_and_b32_e32 v233, 0xffff0000, v233
	v_fmac_f32_e32 v60, s92, v177
	v_fmac_f32_e32 v61, s92, v230
	v_fmac_f32_e32 v62, s92, v180
	v_fmac_f32_e32 v63, s92, v231
	v_fmac_f32_e32 v56, s92, v181
	v_fmac_f32_e32 v57, s92, v232
	v_fmac_f32_e32 v58, s92, v250
	v_fmac_f32_e32 v59, s92, v233
	v_cvt_pk_bf16_f32 v230, v60, v61
	v_cvt_pk_bf16_f32 v231, v62, v63
	v_cvt_pk_bf16_f32 v232, v56, v57
	v_cvt_pk_bf16_f32 v233, v58, v59
	global_store_dwordx4 v176, v[230:233], s[30:31]
	s_waitcnt vmcnt(15)
	v_lshlrev_b32_e32 v177, 16, v234
	v_lshlrev_b32_e32 v180, 16, v235
	v_lshlrev_b32_e32 v181, 16, v236
	v_lshlrev_b32_e32 v250, 16, v237
	v_and_b32_e32 v234, 0xffff0000, v234
	v_and_b32_e32 v235, 0xffff0000, v235
	v_and_b32_e32 v236, 0xffff0000, v236
	v_and_b32_e32 v237, 0xffff0000, v237
	v_fmac_f32_e32 v52, s92, v177
	v_fmac_f32_e32 v53, s92, v234
	v_fmac_f32_e32 v54, s92, v180
	v_fmac_f32_e32 v55, s92, v235
	v_fmac_f32_e32 v48, s92, v181
	v_fmac_f32_e32 v49, s92, v236
	v_fmac_f32_e32 v50, s92, v250
	v_fmac_f32_e32 v51, s92, v237
	v_cvt_pk_bf16_f32 v234, v52, v53
	v_cvt_pk_bf16_f32 v235, v54, v55
	v_cvt_pk_bf16_f32 v236, v48, v49
	v_cvt_pk_bf16_f32 v237, v50, v51
	global_store_dwordx4 v176, v[234:237], s[30:31] offset:256
	s_add_u32 s30, s22, 0x48000
	s_addc_u32 s31, s23, 0
	s_waitcnt vmcnt(15)
	v_lshlrev_b32_e32 v177, 16, v238
	v_lshlrev_b32_e32 v180, 16, v239
	v_lshlrev_b32_e32 v181, 16, v240
	v_lshlrev_b32_e32 v250, 16, v241
	v_and_b32_e32 v238, 0xffff0000, v238
	v_and_b32_e32 v239, 0xffff0000, v239
	v_and_b32_e32 v240, 0xffff0000, v240
	v_and_b32_e32 v241, 0xffff0000, v241
	v_fmac_f32_e32 v44, s92, v177
	v_fmac_f32_e32 v45, s92, v238
	v_fmac_f32_e32 v46, s92, v180
	v_fmac_f32_e32 v47, s92, v239
	v_fmac_f32_e32 v40, s92, v181
	v_fmac_f32_e32 v41, s92, v240
	v_fmac_f32_e32 v42, s92, v250
	v_fmac_f32_e32 v43, s92, v241
	v_cvt_pk_bf16_f32 v238, v44, v45
	v_cvt_pk_bf16_f32 v239, v46, v47
	v_cvt_pk_bf16_f32 v240, v40, v41
	v_cvt_pk_bf16_f32 v241, v42, v43
	global_store_dwordx4 v176, v[238:241], s[30:31]
	s_waitcnt vmcnt(15)
	v_lshlrev_b32_e32 v177, 16, v242
	v_lshlrev_b32_e32 v180, 16, v243
	v_lshlrev_b32_e32 v181, 16, v244
	v_lshlrev_b32_e32 v250, 16, v245
	v_and_b32_e32 v242, 0xffff0000, v242
	v_and_b32_e32 v243, 0xffff0000, v243
	v_and_b32_e32 v244, 0xffff0000, v244
	v_and_b32_e32 v245, 0xffff0000, v245
	v_fmac_f32_e32 v36, s92, v177
	v_fmac_f32_e32 v37, s92, v242
	v_fmac_f32_e32 v38, s92, v180
	v_fmac_f32_e32 v39, s92, v243
	v_fmac_f32_e32 v32, s92, v181
	v_fmac_f32_e32 v33, s92, v244
	v_fmac_f32_e32 v34, s92, v250
	v_fmac_f32_e32 v35, s92, v245
	v_cvt_pk_bf16_f32 v242, v36, v37
	v_cvt_pk_bf16_f32 v243, v38, v39
	v_cvt_pk_bf16_f32 v244, v32, v33
	v_cvt_pk_bf16_f32 v245, v34, v35
	global_store_dwordx4 v176, v[242:245], s[30:31] offset:256
	s_add_u32 s30, s22, 0x50000
	s_addc_u32 s31, s23, 0
	s_waitcnt vmcnt(15)
; __device__ __forceinline__ unsigned cvtpk(float lo, float hi) { f32x2_t v = {lo, hi}; bf16x2_t b = __builtin_convertvector(v, bf16x2_t); return __builtin_bit_cast(unsigned, b); }
;     __device__ __forceinline__ void operator()(const f32x4 (&acc)[2][2][4][2], const pg8::Unit& u, int wr, int wc, int fr, int fq) const {
;     ...
;                     const unsigned so = rl * sstr + (cb + (unsigned)(bj * 128)) * 2u, dofs = rl * 4096u + (cb + (unsigned)(bj * 128)) * 4u;
;                     const u32x4 xb = *(const u32x4*)(sbase + so);
;                     f32x4 x0, x1;
;                     x0[0] = __uint_as_float(xb.x << 16); x0[1] = __uint_as_float(xb.x & 0xffff0000u); x0[2] = __uint_as_float(xb.y << 16); x0[3] = __uint_as_float(xb.y & 0xffff0000u);
;                     x1[0] = __uint_as_float(xb.z << 16); x1[1] = __uint_as_float(xb.z & 0xffff0000u); x1[2] = __uint_as_float(xb.w << 16); x1[3] = __uint_as_float(xb.w & 0xffff0000u);
;                     const f32x4 y0 = x0 * DN_ALPHA + acc[ai][bj][m][0], y1 = x1 * DN_ALPHA + acc[ai][bj][m][1];
;                     if (part) { *(f32x4*)((char*)dbase + dofs) = y0; *(f32x4*)((char*)dbase + dofs + 16) = y1; }
;                     else { u32x4 w; w.x = cvtpk(y0[0], y0[1]); w.y = cvtpk(y0[2], y0[3]); w.z = cvtpk(y1[0], y1[1]); w.w = cvtpk(y1[2], y1[3]); *(u32x4*)((char*)dbase + (dofs >> 1)) = w; }
;                     asm volatile("" ::: "memory");
;                 }
	v_lshlrev_b32_e32 v177, 16, v246
	v_lshlrev_b32_e32 v180, 16, v247
	v_lshlrev_b32_e32 v181, 16, v248
	v_lshlrev_b32_e32 v250, 16, v249
	v_and_b32_e32 v246, 0xffff0000, v246
	v_and_b32_e32 v247, 0xffff0000, v247
	v_and_b32_e32 v248, 0xffff0000, v248
	v_and_b32_e32 v249, 0xffff0000, v249
	v_fmac_f32_e32 v28, s92, v177
	v_fmac_f32_e32 v29, s92, v246
	v_fmac_f32_e32 v30, s92, v180
	v_fmac_f32_e32 v31, s92, v247
	v_fmac_f32_e32 v24, s92, v181
	v_fmac_f32_e32 v25, s92, v248
	v_fmac_f32_e32 v26, s92, v250
	v_fmac_f32_e32 v27, s92, v249
	v_cvt_pk_bf16_f32 v246, v28, v29
	v_cvt_pk_bf16_f32 v247, v30, v31
	v_cvt_pk_bf16_f32 v248, v24, v25
	v_cvt_pk_bf16_f32 v249, v26, v27
	global_store_dwordx4 v176, v[246:249], s[30:31]
	s_waitcnt vmcnt(15)
	v_lshlrev_b32_e32 v177, 16, v164
	v_lshlrev_b32_e32 v180, 16, v165
	v_lshlrev_b32_e32 v181, 16, v166
	v_lshlrev_b32_e32 v250, 16, v167
	v_and_b32_e32 v164, 0xffff0000, v164
	v_and_b32_e32 v165, 0xffff0000, v165
	v_and_b32_e32 v166, 0xffff0000, v166
	v_and_b32_e32 v167, 0xffff0000, v167
	v_fmac_f32_e32 v20, s92, v177
	v_fmac_f32_e32 v21, s92, v164
	v_fmac_f32_e32 v22, s92, v180
	v_fmac_f32_e32 v23, s92, v165
	v_fmac_f32_e32 v16, s92, v181
	v_fmac_f32_e32 v17, s92, v166
	v_fmac_f32_e32 v18, s92, v250
	v_fmac_f32_e32 v19, s92, v167
	v_cvt_pk_bf16_f32 v164, v20, v21
	v_cvt_pk_bf16_f32 v165, v22, v23
	v_cvt_pk_bf16_f32 v166, v16, v17
	v_cvt_pk_bf16_f32 v167, v18, v19
	global_store_dwordx4 v176, v[164:167], s[30:31] offset:256
	s_add_u32 s30, s22, 0x58000
	s_addc_u32 s31, s23, 0
	s_waitcnt vmcnt(15)
	v_lshlrev_b32_e32 v177, 16, v168
	v_lshlrev_b32_e32 v180, 16, v169
	v_lshlrev_b32_e32 v181, 16, v170
	v_lshlrev_b32_e32 v250, 16, v171
	v_and_b32_e32 v168, 0xffff0000, v168
	v_and_b32_e32 v169, 0xffff0000, v169
	v_and_b32_e32 v170, 0xffff0000, v170
	v_and_b32_e32 v171, 0xffff0000, v171
	v_fmac_f32_e32 v12, s92, v177
	v_fmac_f32_e32 v13, s92, v168
	v_fmac_f32_e32 v14, s92, v180
	v_fmac_f32_e32 v15, s92, v169
	v_fmac_f32_e32 v8, s92, v181
	v_fmac_f32_e32 v9, s92, v170
	v_fmac_f32_e32 v10, s92, v250
	v_fmac_f32_e32 v11, s92, v171
	v_cvt_pk_bf16_f32 v168, v12, v13
	v_cvt_pk_bf16_f32 v169, v14, v15
	v_cvt_pk_bf16_f32 v170, v8, v9
	v_cvt_pk_bf16_f32 v171, v10, v11
	global_store_dwordx4 v176, v[168:171], s[30:31]
	s_waitcnt vmcnt(15)
	v_lshlrev_b32_e32 v177, 16, v172
	v_lshlrev_b32_e32 v180, 16, v173
	v_lshlrev_b32_e32 v181, 16, v174
	v_lshlrev_b32_e32 v250, 16, v175
	v_and_b32_e32 v172, 0xffff0000, v172
	v_and_b32_e32 v173, 0xffff0000, v173
	v_and_b32_e32 v174, 0xffff0000, v174
	v_and_b32_e32 v175, 0xffff0000, v175
	v_fmac_f32_e32 v4, s92, v177
	v_fmac_f32_e32 v5, s92, v172
	v_fmac_f32_e32 v6, s92, v180
	v_fmac_f32_e32 v7, s92, v173
	v_fmac_f32_e32 v0, s92, v181
	v_fmac_f32_e32 v1, s92, v174
	v_fmac_f32_e32 v2, s92, v250
	v_fmac_f32_e32 v3, s92, v175
	v_cvt_pk_bf16_f32 v172, v4, v5
	v_cvt_pk_bf16_f32 v173, v6, v7
	v_cvt_pk_bf16_f32 v174, v0, v1
	v_cvt_pk_bf16_f32 v175, v2, v3
	global_store_dwordx4 v176, v[172:175], s[30:31] offset:256
	s_branch .Lerwo_done
.Lerwo_part:
	v_lshl_add_u32 v176, v165, 2, v140
	global_store_dwordx4 v176, v[124:127], s[22:23]
	global_store_dwordx4 v176, v[120:123], s[22:23] offset:16
	global_store_dwordx4 v176, v[116:119], s[22:23] offset:512
	global_store_dwordx4 v176, v[112:115], s[22:23] offset:528
	s_add_u32 s30, s22, 0x10000
	s_addc_u32 s31, s23, 0
	global_store_dwordx4 v176, v[108:111], s[30:31]
	global_store_dwordx4 v176, v[104:107], s[30:31] offset:16
	global_store_dwordx4 v176, v[100:103], s[30:31] offset:512
	global_store_dwordx4 v176, v[96:99], s[30:31] offset:528
	s_add_u32 s30, s22, 0x20000
	s_addc_u32 s31, s23, 0
	global_store_dwordx4 v176, v[92:95], s[30:31]
	global_store_dwordx4 v176, v[88:91], s[30:31] offset:16
	global_store_dwordx4 v176, v[84:87], s[30:31] offset:512
	global_store_dwordx4 v176, v[80:83], s[30:31] offset:528
	s_add_u32 s30, s22, 0x30000
	s_addc_u32 s31, s23, 0
	global_store_dwordx4 v176, v[76:79], s[30:31]
	global_store_dwordx4 v176, v[72:75], s[30:31] offset:16
	global_store_dwordx4 v176, v[68:71], s[30:31] offset:512
	global_store_dwordx4 v176, v[64:67], s[30:31] offset:528
	s_add_u32 s30, s22, 0x80000
	s_addc_u32 s31, s23, 0
	global_store_dwordx4 v176, v[60:63], s[30:31]
	global_store_dwordx4 v176, v[56:59], s[30:31] offset:16
	global_store_dwordx4 v176, v[52:55], s[30:31] offset:512
	global_store_dwordx4 v176, v[48:51], s[30:31] offset:528
	s_add_u32 s30, s22, 0x90000
	s_addc_u32 s31, s23, 0
	global_store_dwordx4 v176, v[44:47], s[30:31]
	global_store_dwordx4 v176, v[40:43], s[30:31] offset:16
	global_store_dwordx4 v176, v[36:39], s[30:31] offset:512
	global_store_dwordx4 v176, v[32:35], s[30:31] offset:528
	s_add_u32 s30, s22, 0xa0000
	s_addc_u32 s31, s23, 0
	global_store_dwordx4 v176, v[28:31], s[30:31]
	global_store_dwordx4 v176, v[24:27], s[30:31] offset:16
	global_store_dwordx4 v176, v[20:23], s[30:31] offset:512
	global_store_dwordx4 v176, v[16:19], s[30:31] offset:528
	s_add_u32 s30, s22, 0xb0000
	s_addc_u32 s31, s23, 0
	global_store_dwordx4 v176, v[12:15], s[30:31]
	global_store_dwordx4 v176, v[8:11], s[30:31] offset:16
	global_store_dwordx4 v176, v[4:7], s[30:31] offset:512
	global_store_dwordx4 v176, v[0:3], s[30:31] offset:528
.Lerwo_done:
.LBB0_452:
	s_andn2_b64 vcc, exec, s[10:11]
	s_mov_b64 s[6:7], -1
	s_cbranch_vccnz .LBB0_369
	s_andn2_b64 vcc, exec, s[0:1]
	s_cbranch_vccnz .LBB0_368
	s_barrier
	s_branch .LBB0_368

; __device__ __forceinline__ unsigned cvtpk(float lo, float hi) { f32x2_t v = {lo, hi}; bf16x2_t b = __builtin_convertvector(v, bf16x2_t); return __builtin_bit_cast(unsigned, b); }
;     __device__ __forceinline__ void operator()(const f32x4 (&acc)[2][2][4][2], const pg8::Unit& u, int wr, int wc, int fr, int fq) const {
;         const bool part = u.part >= 0;
;         float* dbase = part ? (float*)(ws + WS_PART) + (size_t)u.part * MS * 1024 : (float*)(ws + WS_XF + (size_t)u.pm * 256 * 2048);
;         const unsigned char* sbase = part ? ws + WS_ZERO : ws + WS_XB + (size_t)u.pm * 256 * 2048;
;         const unsigned sstr = part ? 0u : 2048u;
;         const unsigned cb = (unsigned)(u.pn * 256 + wc * 32 + 8 * fq);
; #pragma unroll
;         for (int ai = 0; ai < 2; ++ai)
; #pragma unroll
;             for (int m = 0; m < 4; ++m) {
;                 const unsigned rl = (unsigned)(ai * 128 + wr * 64 + m * 16 + fr);
; #pragma unroll
;                 for (int bj = 0; bj < 2; ++bj) {
;                     const unsigned so = rl * sstr + (cb + (unsigned)(bj * 128)) * 2u, dofs = rl * 4096u + (cb + (unsigned)(bj * 128)) * 4u;
;                     const u32x4 xb = *(const u32x4*)(sbase + so);
;                     f32x4 x0, x1;
;                     x0[0] = __uint_as_float(xb.x << 16); x0[1] = __uint_as_float(xb.x & 0xffff0000u); x0[2] = __uint_as_float(xb.y << 16); x0[3] = __uint_as_float(xb.y & 0xffff0000u);
;                     x1[0] = __uint_as_float(xb.z << 16); x1[1] = __uint_as_float(xb.z & 0xffff0000u); x1[2] = __uint_as_float(xb.w << 16); x1[3] = __uint_as_float(xb.w & 0xffff0000u);
;                     const f32x4 y0 = x0 * DN_ALPHA + acc[ai][bj][m][0], y1 = x1 * DN_ALPHA + acc[ai][bj][m][1];
;                     if (part) { *(f32x4*)((char*)dbase + dofs) = y0; *(f32x4*)((char*)dbase + dofs + 16) = y1; }
;                     else { u32x4 w; w.x = cvtpk(y0[0], y0[1]); w.y = cvtpk(y0[2], y0[3]); w.z = cvtpk(y1[0], y1[1]); w.w = cvtpk(y1[2], y1[3]); *(u32x4*)((char*)dbase + (dofs >> 1)) = w; }
;                     asm volatile("" ::: "memory");
;                 }
.LBB0_696:
	s_add_u32 s7, s49, s28
	s_addc_u32 s20, s50, s29
	v_lshl_or_b32 v165, s22, 8, v160
	s_and_b64 s[4:5], s[4:5], exec
	v_mul_lo_u32 v164, s15, v138
	v_lshlrev_b32_e32 v162, 1, v165
	s_cselect_b32 s21, s52, s20
	s_cselect_b32 s20, s51, s7
	v_add_u32_e32 v163, v164, v162
	s_and_b64 vcc, exec, s[26:27]
	s_cbranch_vccz .Lerdn_part
	v_lshrrev_b32_e32 v176, 1, v140
	v_add_u32_e32 v176, v176, v162
	global_load_dwordx4 v[198:201], v163, s[20:21]
	global_load_dwordx4 v[202:205], v163, s[20:21] offset:256
	s_add_u32 s28, s20, 0x8000
	s_addc_u32 s29, s21, 0
	global_load_dwordx4 v[206:209], v163, s[28:29]
	global_load_dwordx4 v[210:213], v163, s[28:29] offset:256
	s_add_u32 s28, s20, 0x10000
	s_addc_u32 s29, s21, 0
	global_load_dwordx4 v[214:217], v163, s[28:29]
	global_load_dwordx4 v[218:221], v163, s[28:29] offset:256
	s_add_u32 s28, s20, 0x18000
	s_addc_u32 s29, s21, 0
	global_load_dwordx4 v[222:225], v163, s[28:29]
	global_load_dwordx4 v[226:229], v163, s[28:29] offset:256
	s_add_u32 s28, s20, 0x40000
	s_addc_u32 s29, s21, 0
	global_load_dwordx4 v[230:233], v163, s[28:29]
	global_load_dwordx4 v[234:237], v163, s[28:29] offset:256
	s_add_u32 s28, s20, 0x48000
	s_addc_u32 s29, s21, 0
	global_load_dwordx4 v[238:241], v163, s[28:29]
	global_load_dwordx4 v[242:245], v163, s[28:29] offset:256
	s_add_u32 s28, s20, 0x50000
	s_addc_u32 s29, s21, 0
	global_load_dwordx4 v[246:249], v163, s[28:29]
	global_load_dwordx4 v[164:167], v163, s[28:29] offset:256
	s_add_u32 s28, s20, 0x58000
	s_addc_u32 s29, s21, 0
	global_load_dwordx4 v[168:171], v163, s[28:29]
	global_load_dwordx4 v[172:175], v163, s[28:29] offset:256
	s_waitcnt vmcnt(15)
	v_lshlrev_b32_e32 v177, 16, v198
	v_lshlrev_b32_e32 v180, 16, v199
	v_lshlrev_b32_e32 v181, 16, v200
	v_lshlrev_b32_e32 v250, 16, v201
	v_and_b32_e32 v198, 0xffff0000, v198
	v_and_b32_e32 v199, 0xffff0000, v199
	v_and_b32_e32 v200, 0xffff0000, v200
	v_and_b32_e32 v201, 0xffff0000, v201
	v_fmac_f32_e32 v124, s92, v177
	v_fmac_f32_e32 v125, s92, v198
	v_fmac_f32_e32 v126, s92, v180
	v_fmac_f32_e32 v127, s92, v199
	v_fmac_f32_e32 v120, s92, v181
	v_fmac_f32_e32 v121, s92, v200
	v_fmac_f32_e32 v122, s92, v250
	v_fmac_f32_e32 v123, s92, v201
	v_cvt_pk_bf16_f32 v198, v124, v125
	v_cvt_pk_bf16_f32 v199, v126, v127
	v_cvt_pk_bf16_f32 v200, v120, v121
	v_cvt_pk_bf16_f32 v201, v122, v123
	global_store_dwordx4 v176, v[198:201], s[24:25]
	s_waitcnt vmcnt(15)
	v_lshlrev_b32_e32 v177, 16, v202
	v_lshlrev_b32_e32 v180, 16, v203
	v_lshlrev_b32_e32 v181, 16, v204
	v_lshlrev_b32_e32 v250, 16, v205
	v_and_b32_e32 v202, 0xffff0000, v202
	v_and_b32_e32 v203, 0xffff0000, v203
	v_and_b32_e32 v204, 0xffff0000, v204
	v_and_b32_e32 v205, 0xffff0000, v205
	v_fmac_f32_e32 v116, s92, v177
	v_fmac_f32_e32 v117, s92, v202
	v_fmac_f32_e32 v118, s92, v180
	v_fmac_f32_e32 v119, s92, v203
	v_fmac_f32_e32 v112, s92, v181
	v_fmac_f32_e32 v113, s92, v204
	v_fmac_f32_e32 v114, s92, v250
	v_fmac_f32_e32 v115, s92, v205
	v_cvt_pk_bf16_f32 v202, v116, v117
	v_cvt_pk_bf16_f32 v203, v118, v119
	v_cvt_pk_bf16_f32 v204, v112, v113
	v_cvt_pk_bf16_f32 v205, v114, v115
	global_store_dwordx4 v176, v[202:205], s[24:25] offset:256
	s_add_u32 s30, s24, 0x8000
	s_addc_u32 s31, s25, 0
	s_waitcnt vmcnt(15)
	v_lshlrev_b32_e32 v177, 16, v206
	v_lshlrev_b32_e32 v180, 16, v207
	v_lshlrev_b32_e32 v181, 16, v208
	v_lshlrev_b32_e32 v250, 16, v209
	v_and_b32_e32 v206, 0xffff0000, v206
	v_and_b32_e32 v207, 0xffff0000, v207
	v_and_b32_e32 v208, 0xffff0000, v208
	v_and_b32_e32 v209, 0xffff0000, v209
	v_fmac_f32_e32 v108, s92, v177
	v_fmac_f32_e32 v109, s92, v206
	v_fmac_f32_e32 v110, s92, v180
	v_fmac_f32_e32 v111, s92, v207
	v_fmac_f32_e32 v104, s92, v181
	v_fmac_f32_e32 v105, s92, v208
	v_fmac_f32_e32 v106, s92, v250
	v_fmac_f32_e32 v107, s92, v209
	v_cvt_pk_bf16_f32 v206, v108, v109
	v_cvt_pk_bf16_f32 v207, v110, v111
	v_cvt_pk_bf16_f32 v208, v104, v105
	v_cvt_pk_bf16_f32 v209, v106, v107
	global_store_dwordx4 v176, v[206:209], s[30:31]
	s_waitcnt vmcnt(15)
	v_lshlrev_b32_e32 v177, 16, v210
	v_lshlrev_b32_e32 v180, 16, v211
	v_lshlrev_b32_e32 v181, 16, v212
	v_lshlrev_b32_e32 v250, 16, v213
	v_and_b32_e32 v210, 0xffff0000, v210
	v_and_b32_e32 v211, 0xffff0000, v211
	v_and_b32_e32 v212, 0xffff0000, v212
	v_and_b32_e32 v213, 0xffff0000, v213
	v_fmac_f32_e32 v100, s92, v177
	v_fmac_f32_e32 v101, s92, v210
	v_fmac_f32_e32 v102, s92, v180
	v_fmac_f32_e32 v103, s92, v211
	v_fmac_f32_e32 v96, s92, v181
	v_fmac_f32_e32 v97, s92, v212
	v_fmac_f32_e32 v98, s92, v250
	v_fmac_f32_e32 v99, s92, v213
	v_cvt_pk_bf16_f32 v210, v100, v101
	v_cvt_pk_bf16_f32 v211, v102, v103
	v_cvt_pk_bf16_f32 v212, v96, v97
	v_cvt_pk_bf16_f32 v213, v98, v99
	global_store_dwordx4 v176, v[210:213], s[30:31] offset:256
	s_add_u32 s30, s24, 0x10000
	s_addc_u32 s31, s25, 0
	s_waitcnt vmcnt(15)
	v_lshlrev_b32_e32 v177, 16, v214
	v_lshlrev_b32_e32 v180, 16, v215
	v_lshlrev_b32_e32 v181, 16, v216
	v_lshlrev_b32_e32 v250, 16, v217
	v_and_b32_e32 v214, 0xffff0000, v214
	v_and_b32_e32 v215, 0xffff0000, v215
	v_and_b32_e32 v216, 0xffff0000, v216
	v_and_b32_e32 v217, 0xffff0000, v217
	v_fmac_f32_e32 v92, s92, v177
	v_fmac_f32_e32 v93, s92, v214
	v_fmac_f32_e32 v94, s92, v180
	v_fmac_f32_e32 v95, s92, v215
	v_fmac_f32_e32 v88, s92, v181
	v_fmac_f32_e32 v89, s92, v216
	v_fmac_f32_e32 v90, s92, v250
	v_fmac_f32_e32 v91, s92, v217
	v_cvt_pk_bf16_f32 v214, v92, v93
	v_cvt_pk_bf16_f32 v215, v94, v95
	v_cvt_pk_bf16_f32 v216, v88, v89
	v_cvt_pk_bf16_f32 v217, v90, v91
	global_store_dwordx4 v176, v[214:217], s[30:31]
	s_waitcnt vmcnt(15)
; __device__ __forceinline__ unsigned cvtpk(float lo, float hi) { f32x2_t v = {lo, hi}; bf16x2_t b = __builtin_convertvector(v, bf16x2_t); return __builtin_bit_cast(unsigned, b); }
;     __device__ __forceinline__ void operator()(const f32x4 (&acc)[2][2][4][2], const pg8::Unit& u, int wr, int wc, int fr, int fq) const {
;     ...
;                     const unsigned so = rl * sstr + (cb + (unsigned)(bj * 128)) * 2u, dofs = rl * 4096u + (cb + (unsigned)(bj * 128)) * 4u;
;                     const u32x4 xb = *(const u32x4*)(sbase + so);
;                     f32x4 x0, x1;
;                     x0[0] = __uint_as_float(xb.x << 16); x0[1] = __uint_as_float(xb.x & 0xffff0000u); x0[2] = __uint_as_float(xb.y << 16); x0[3] = __uint_as_float(xb.y & 0xffff0000u);
;                     x1[0] = __uint_as_float(xb.z << 16); x1[1] = __uint_as_float(xb.z & 0xffff0000u); x1[2] = __uint_as_float(xb.w << 16); x1[3] = __uint_as_float(xb.w & 0xffff0000u);
;                     const f32x4 y0 = x0 * DN_ALPHA + acc[ai][bj][m][0], y1 = x1 * DN_ALPHA + acc[ai][bj][m][1];
;                     if (part) { *(f32x4*)((char*)dbase + dofs) = y0; *(f32x4*)((char*)dbase + dofs + 16) = y1; }
;                     else { u32x4 w; w.x = cvtpk(y0[0], y0[1]); w.y = cvtpk(y0[2], y0[3]); w.z = cvtpk(y1[0], y1[1]); w.w = cvtpk(y1[2], y1[3]); *(u32x4*)((char*)dbase + (dofs >> 1)) = w; }
	v_lshlrev_b32_e32 v177, 16, v218
	v_lshlrev_b32_e32 v180, 16, v219
	v_lshlrev_b32_e32 v181, 16, v220
	v_lshlrev_b32_e32 v250, 16, v221
	v_and_b32_e32 v218, 0xffff0000, v218
	v_and_b32_e32 v219, 0xffff0000, v219
	v_and_b32_e32 v220, 0xffff0000, v220
	v_and_b32_e32 v221, 0xffff0000, v221
	v_fmac_f32_e32 v84, s92, v177
	v_fmac_f32_e32 v85, s92, v218
	v_fmac_f32_e32 v86, s92, v180
	v_fmac_f32_e32 v87, s92, v219
	v_fmac_f32_e32 v80, s92, v181
	v_fmac_f32_e32 v81, s92, v220
	v_fmac_f32_e32 v82, s92, v250
	v_fmac_f32_e32 v83, s92, v221
	v_cvt_pk_bf16_f32 v218, v84, v85
	v_cvt_pk_bf16_f32 v219, v86, v87
	v_cvt_pk_bf16_f32 v220, v80, v81
	v_cvt_pk_bf16_f32 v221, v82, v83
	global_store_dwordx4 v176, v[218:221], s[30:31] offset:256
	s_add_u32 s30, s24, 0x18000
	s_addc_u32 s31, s25, 0
	s_waitcnt vmcnt(15)
	v_lshlrev_b32_e32 v177, 16, v222
	v_lshlrev_b32_e32 v180, 16, v223
	v_lshlrev_b32_e32 v181, 16, v224
	v_lshlrev_b32_e32 v250, 16, v225
	v_and_b32_e32 v222, 0xffff0000, v222
	v_and_b32_e32 v223, 0xffff0000, v223
	v_and_b32_e32 v224, 0xffff0000, v224
	v_and_b32_e32 v225, 0xffff0000, v225
	v_fmac_f32_e32 v76, s92, v177
	v_fmac_f32_e32 v77, s92, v222
	v_fmac_f32_e32 v78, s92, v180
	v_fmac_f32_e32 v79, s92, v223
	v_fmac_f32_e32 v72, s92, v181
	v_fmac_f32_e32 v73, s92, v224
	v_fmac_f32_e32 v74, s92, v250
	v_fmac_f32_e32 v75, s92, v225
	v_cvt_pk_bf16_f32 v222, v76, v77
	v_cvt_pk_bf16_f32 v223, v78, v79
	v_cvt_pk_bf16_f32 v224, v72, v73
	v_cvt_pk_bf16_f32 v225, v74, v75
	global_store_dwordx4 v176, v[222:225], s[30:31]
	s_waitcnt vmcnt(15)
	v_lshlrev_b32_e32 v177, 16, v226
	v_lshlrev_b32_e32 v180, 16, v227
	v_lshlrev_b32_e32 v181, 16, v228
	v_lshlrev_b32_e32 v250, 16, v229
	v_and_b32_e32 v226, 0xffff0000, v226
	v_and_b32_e32 v227, 0xffff0000, v227
	v_and_b32_e32 v228, 0xffff0000, v228
	v_and_b32_e32 v229, 0xffff0000, v229
	v_fmac_f32_e32 v68, s92, v177
	v_fmac_f32_e32 v69, s92, v226
	v_fmac_f32_e32 v70, s92, v180
	v_fmac_f32_e32 v71, s92, v227
	v_fmac_f32_e32 v64, s92, v181
	v_fmac_f32_e32 v65, s92, v228
	v_fmac_f32_e32 v66, s92, v250
	v_fmac_f32_e32 v67, s92, v229
	v_cvt_pk_bf16_f32 v226, v68, v69
	v_cvt_pk_bf16_f32 v227, v70, v71
	v_cvt_pk_bf16_f32 v228, v64, v65
	v_cvt_pk_bf16_f32 v229, v66, v67
	global_store_dwordx4 v176, v[226:229], s[30:31] offset:256
	s_add_u32 s30, s24, 0x40000
	s_addc_u32 s31, s25, 0
	s_waitcnt vmcnt(15)
	v_lshlrev_b32_e32 v177, 16, v230
	v_lshlrev_b32_e32 v180, 16, v231
	v_lshlrev_b32_e32 v181, 16, v232
	v_lshlrev_b32_e32 v250, 16, v233
	v_and_b32_e32 v230, 0xffff0000, v230
	v_and_b32_e32 v231, 0xffff0000, v231
	v_and_b32_e32 v232, 0xffff0000, v232
	v_and_b32_e32 v233, 0xffff0000, v233
	v_fmac_f32_e32 v60, s92, v177
	v_fmac_f32_e32 v61, s92, v230
	v_fmac_f32_e32 v62, s92, v180
	v_fmac_f32_e32 v63, s92, v231
	v_fmac_f32_e32 v56, s92, v181
	v_fmac_f32_e32 v57, s92, v232
	v_fmac_f32_e32 v58, s92, v250
	v_fmac_f32_e32 v59, s92, v233
	v_cvt_pk_bf16_f32 v230, v60, v61
	v_cvt_pk_bf16_f32 v231, v62, v63
	v_cvt_pk_bf16_f32 v232, v56, v57
	v_cvt_pk_bf16_f32 v233, v58, v59
	global_store_dwordx4 v176, v[230:233], s[30:31]
	s_waitcnt vmcnt(15)
	v_lshlrev_b32_e32 v177, 16, v234
	v_lshlrev_b32_e32 v180, 16, v235
	v_lshlrev_b32_e32 v181, 16, v236
	v_lshlrev_b32_e32 v250, 16, v237
	v_and_b32_e32 v234, 0xffff0000, v234
	v_and_b32_e32 v235, 0xffff0000, v235
	v_and_b32_e32 v236, 0xffff0000, v236
	v_and_b32_e32 v237, 0xffff0000, v237
	v_fmac_f32_e32 v52, s92, v177
	v_fmac_f32_e32 v53, s92, v234
	v_fmac_f32_e32 v54, s92, v180
	v_fmac_f32_e32 v55, s92, v235
	v_fmac_f32_e32 v48, s92, v181
	v_fmac_f32_e32 v49, s92, v236
	v_fmac_f32_e32 v50, s92, v250
	v_fmac_f32_e32 v51, s92, v237
	v_cvt_pk_bf16_f32 v234, v52, v53
	v_cvt_pk_bf16_f32 v235, v54, v55
	v_cvt_pk_bf16_f32 v236, v48, v49
	v_cvt_pk_bf16_f32 v237, v50, v51
	global_store_dwordx4 v176, v[234:237], s[30:31] offset:256
	s_add_u32 s30, s24, 0x48000
	s_addc_u32 s31, s25, 0
	s_waitcnt vmcnt(15)
	v_lshlrev_b32_e32 v177, 16, v238
	v_lshlrev_b32_e32 v180, 16, v239
	v_lshlrev_b32_e32 v181, 16, v240
	v_lshlrev_b32_e32 v250, 16, v241
	v_and_b32_e32 v238, 0xffff0000, v238
	v_and_b32_e32 v239, 0xffff0000, v239
	v_and_b32_e32 v240, 0xffff0000, v240
	v_and_b32_e32 v241, 0xffff0000, v241
	v_fmac_f32_e32 v44, s92, v177
	v_fmac_f32_e32 v45, s92, v238
	v_fmac_f32_e32 v46, s92, v180
	v_fmac_f32_e32 v47, s92, v239
	v_fmac_f32_e32 v40, s92, v181
	v_fmac_f32_e32 v41, s92, v240
	v_fmac_f32_e32 v42, s92, v250
	v_fmac_f32_e32 v43, s92, v241
	v_cvt_pk_bf16_f32 v238, v44, v45
	v_cvt_pk_bf16_f32 v239, v46, v47
	v_cvt_pk_bf16_f32 v240, v40, v41
	v_cvt_pk_bf16_f32 v241, v42, v43
	global_store_dwordx4 v176, v[238:241], s[30:31]
	s_waitcnt vmcnt(15)
	v_lshlrev_b32_e32 v177, 16, v242
	v_lshlrev_b32_e32 v180, 16, v243
	v_lshlrev_b32_e32 v181, 16, v244
	v_lshlrev_b32_e32 v250, 16, v245
	v_and_b32_e32 v242, 0xffff0000, v242
	v_and_b32_e32 v243, 0xffff0000, v243
	v_and_b32_e32 v244, 0xffff0000, v244
	v_and_b32_e32 v245, 0xffff0000, v245
	v_fmac_f32_e32 v36, s92, v177
	v_fmac_f32_e32 v37, s92, v242
	v_fmac_f32_e32 v38, s92, v180
	v_fmac_f32_e32 v39, s92, v243
	v_fmac_f32_e32 v32, s92, v181
	v_fmac_f32_e32 v33, s92, v244
	v_fmac_f32_e32 v34, s92, v250
	v_fmac_f32_e32 v35, s92, v245
	v_cvt_pk_bf16_f32 v242, v36, v37
	v_cvt_pk_bf16_f32 v243, v38, v39
	v_cvt_pk_bf16_f32 v244, v32, v33
	v_cvt_pk_bf16_f32 v245, v34, v35
	global_store_dwordx4 v176, v[242:245], s[30:31] offset:256
	s_add_u32 s30, s24, 0x50000
	s_addc_u32 s31, s25, 0
	s_waitcnt vmcnt(15)
; __device__ __forceinline__ unsigned cvtpk(float lo, float hi) { f32x2_t v = {lo, hi}; bf16x2_t b = __builtin_convertvector(v, bf16x2_t); return __builtin_bit_cast(unsigned, b); }
;     __device__ __forceinline__ void operator()(const f32x4 (&acc)[2][2][4][2], const pg8::Unit& u, int wr, int wc, int fr, int fq) const {
;     ...
;                     const unsigned so = rl * sstr + (cb + (unsigned)(bj * 128)) * 2u, dofs = rl * 4096u + (cb + (unsigned)(bj * 128)) * 4u;
;                     const u32x4 xb = *(const u32x4*)(sbase + so);
;                     f32x4 x0, x1;
;                     x0[0] = __uint_as_float(xb.x << 16); x0[1] = __uint_as_float(xb.x & 0xffff0000u); x0[2] = __uint_as_float(xb.y << 16); x0[3] = __uint_as_float(xb.y & 0xffff0000u);
;                     x1[0] = __uint_as_float(xb.z << 16); x1[1] = __uint_as_float(xb.z & 0xffff0000u); x1[2] = __uint_as_float(xb.w << 16); x1[3] = __uint_as_float(xb.w & 0xffff0000u);
;                     const f32x4 y0 = x0 * DN_ALPHA + acc[ai][bj][m][0], y1 = x1 * DN_ALPHA + acc[ai][bj][m][1];
;                     if (part) { *(f32x4*)((char*)dbase + dofs) = y0; *(f32x4*)((char*)dbase + dofs + 16) = y1; }
;                     else { u32x4 w; w.x = cvtpk(y0[0], y0[1]); w.y = cvtpk(y0[2], y0[3]); w.z = cvtpk(y1[0], y1[1]); w.w = cvtpk(y1[2], y1[3]); *(u32x4*)((char*)dbase + (dofs >> 1)) = w; }
;                     asm volatile("" ::: "memory");
;                 }
	v_lshlrev_b32_e32 v177, 16, v246
	v_lshlrev_b32_e32 v180, 16, v247
	v_lshlrev_b32_e32 v181, 16, v248
	v_lshlrev_b32_e32 v250, 16, v249
	v_and_b32_e32 v246, 0xffff0000, v246
	v_and_b32_e32 v247, 0xffff0000, v247
	v_and_b32_e32 v248, 0xffff0000, v248
	v_and_b32_e32 v249, 0xffff0000, v249
	v_fmac_f32_e32 v28, s92, v177
	v_fmac_f32_e32 v29, s92, v246
	v_fmac_f32_e32 v30, s92, v180
	v_fmac_f32_e32 v31, s92, v247
	v_fmac_f32_e32 v24, s92, v181
	v_fmac_f32_e32 v25, s92, v248
	v_fmac_f32_e32 v26, s92, v250
	v_fmac_f32_e32 v27, s92, v249
	v_cvt_pk_bf16_f32 v246, v28, v29
	v_cvt_pk_bf16_f32 v247, v30, v31
	v_cvt_pk_bf16_f32 v248, v24, v25
	v_cvt_pk_bf16_f32 v249, v26, v27
	global_store_dwordx4 v176, v[246:249], s[30:31]
	s_waitcnt vmcnt(15)
	v_lshlrev_b32_e32 v177, 16, v164
	v_lshlrev_b32_e32 v180, 16, v165
	v_lshlrev_b32_e32 v181, 16, v166
	v_lshlrev_b32_e32 v250, 16, v167
	v_and_b32_e32 v164, 0xffff0000, v164
	v_and_b32_e32 v165, 0xffff0000, v165
	v_and_b32_e32 v166, 0xffff0000, v166
	v_and_b32_e32 v167, 0xffff0000, v167
	v_fmac_f32_e32 v20, s92, v177
	v_fmac_f32_e32 v21, s92, v164
	v_fmac_f32_e32 v22, s92, v180
	v_fmac_f32_e32 v23, s92, v165
	v_fmac_f32_e32 v16, s92, v181
	v_fmac_f32_e32 v17, s92, v166
	v_fmac_f32_e32 v18, s92, v250
	v_fmac_f32_e32 v19, s92, v167
	v_cvt_pk_bf16_f32 v164, v20, v21
	v_cvt_pk_bf16_f32 v165, v22, v23
	v_cvt_pk_bf16_f32 v166, v16, v17
	v_cvt_pk_bf16_f32 v167, v18, v19
	global_store_dwordx4 v176, v[164:167], s[30:31] offset:256
	s_add_u32 s30, s24, 0x58000
	s_addc_u32 s31, s25, 0
	s_waitcnt vmcnt(15)
	v_lshlrev_b32_e32 v177, 16, v168
	v_lshlrev_b32_e32 v180, 16, v169
	v_lshlrev_b32_e32 v181, 16, v170
	v_lshlrev_b32_e32 v250, 16, v171
	v_and_b32_e32 v168, 0xffff0000, v168
	v_and_b32_e32 v169, 0xffff0000, v169
	v_and_b32_e32 v170, 0xffff0000, v170
	v_and_b32_e32 v171, 0xffff0000, v171
	v_fmac_f32_e32 v12, s92, v177
	v_fmac_f32_e32 v13, s92, v168
	v_fmac_f32_e32 v14, s92, v180
	v_fmac_f32_e32 v15, s92, v169
	v_fmac_f32_e32 v8, s92, v181
	v_fmac_f32_e32 v9, s92, v170
	v_fmac_f32_e32 v10, s92, v250
	v_fmac_f32_e32 v11, s92, v171
	v_cvt_pk_bf16_f32 v168, v12, v13
	v_cvt_pk_bf16_f32 v169, v14, v15
	v_cvt_pk_bf16_f32 v170, v8, v9
	v_cvt_pk_bf16_f32 v171, v10, v11
	global_store_dwordx4 v176, v[168:171], s[30:31]
	s_waitcnt vmcnt(15)
	v_lshlrev_b32_e32 v177, 16, v172
	v_lshlrev_b32_e32 v180, 16, v173
	v_lshlrev_b32_e32 v181, 16, v174
	v_lshlrev_b32_e32 v250, 16, v175
	v_and_b32_e32 v172, 0xffff0000, v172
	v_and_b32_e32 v173, 0xffff0000, v173
	v_and_b32_e32 v174, 0xffff0000, v174
	v_and_b32_e32 v175, 0xffff0000, v175
	v_fmac_f32_e32 v4, s92, v177
	v_fmac_f32_e32 v5, s92, v172
	v_fmac_f32_e32 v6, s92, v180
	v_fmac_f32_e32 v7, s92, v173
	v_fmac_f32_e32 v0, s92, v181
	v_fmac_f32_e32 v1, s92, v174
	v_fmac_f32_e32 v2, s92, v250
	v_fmac_f32_e32 v3, s92, v175
	v_cvt_pk_bf16_f32 v172, v4, v5
	v_cvt_pk_bf16_f32 v173, v6, v7
	v_cvt_pk_bf16_f32 v174, v0, v1
	v_cvt_pk_bf16_f32 v175, v2, v3
	global_store_dwordx4 v176, v[172:175], s[30:31] offset:256
	s_branch .Lerdn_done
.Lerdn_part:
	v_lshl_add_u32 v176, v165, 2, v140
	global_store_dwordx4 v176, v[124:127], s[24:25]
	global_store_dwordx4 v176, v[120:123], s[24:25] offset:16
	global_store_dwordx4 v176, v[116:119], s[24:25] offset:512
	global_store_dwordx4 v176, v[112:115], s[24:25] offset:528
	s_add_u32 s30, s24, 0x10000
	s_addc_u32 s31, s25, 0
	global_store_dwordx4 v176, v[108:111], s[30:31]
	global_store_dwordx4 v176, v[104:107], s[30:31] offset:16
	global_store_dwordx4 v176, v[100:103], s[30:31] offset:512
	global_store_dwordx4 v176, v[96:99], s[30:31] offset:528
	s_add_u32 s30, s24, 0x20000
	s_addc_u32 s31, s25, 0
	global_store_dwordx4 v176, v[92:95], s[30:31]
	global_store_dwordx4 v176, v[88:91], s[30:31] offset:16
	global_store_dwordx4 v176, v[84:87], s[30:31] offset:512
	global_store_dwordx4 v176, v[80:83], s[30:31] offset:528
	s_add_u32 s30, s24, 0x30000
	s_addc_u32 s31, s25, 0
	global_store_dwordx4 v176, v[76:79], s[30:31]
	global_store_dwordx4 v176, v[72:75], s[30:31] offset:16
	global_store_dwordx4 v176, v[68:71], s[30:31] offset:512
	global_store_dwordx4 v176, v[64:67], s[30:31] offset:528
	s_add_u32 s30, s24, 0x80000
	s_addc_u32 s31, s25, 0
	global_store_dwordx4 v176, v[60:63], s[30:31]
	global_store_dwordx4 v176, v[56:59], s[30:31] offset:16
	global_store_dwordx4 v176, v[52:55], s[30:31] offset:512
	global_store_dwordx4 v176, v[48:51], s[30:31] offset:528
	s_add_u32 s30, s24, 0x90000
	s_addc_u32 s31, s25, 0
	global_store_dwordx4 v176, v[44:47], s[30:31]
	global_store_dwordx4 v176, v[40:43], s[30:31] offset:16
	global_store_dwordx4 v176, v[36:39], s[30:31] offset:512
	global_store_dwordx4 v176, v[32:35], s[30:31] offset:528
	s_add_u32 s30, s24, 0xa0000
	s_addc_u32 s31, s25, 0
	global_store_dwordx4 v176, v[28:31], s[30:31]
	global_store_dwordx4 v176, v[24:27], s[30:31] offset:16
	global_store_dwordx4 v176, v[20:23], s[30:31] offset:512
	global_store_dwordx4 v176, v[16:19], s[30:31] offset:528
	s_add_u32 s30, s24, 0xb0000
	s_addc_u32 s31, s25, 0
	global_store_dwordx4 v176, v[12:15], s[30:31]
	global_store_dwordx4 v176, v[8:11], s[30:31] offset:16
	global_store_dwordx4 v176, v[4:7], s[30:31] offset:512
	global_store_dwordx4 v176, v[0:3], s[30:31] offset:528
.Lerdn_done:
.LBB0_760:
	s_andn2_b64 vcc, exec, s[8:9]
	s_mov_b64 s[4:5], -1
	s_cbranch_vccnz .LBB0_677
	s_andn2_b64 vcc, exec, s[10:11]
	s_cbranch_vccnz .LBB0_676
	s_barrier
	s_branch .LBB0_676
